# pool window pass: IEEE division expansion replaced by rcp + one Newton step (exact for power-of-two counts), LDS reads prefetched
# speedup vs baseline: 1.0022x; 1.0022x over previous
; #define LAS __attribute__((address_space(3)))
; __device__ __forceinline__ unsigned pk_bf16(float lo, float hi) { const f32x2_t v = {lo, hi}; const bf16x2_t b = __builtin_convertvector(v, bf16x2_t); return __builtin_bit_cast(unsigned, b); }
; __device__ __forceinline__ void pool_unit(int tile, int g, const bf16_t* QKVU, const float* state_pool, const bf16_t* POOLWT, bf16_t* MIX, LAS unsigned char* lds) {
;     ...
;         const int c = tid & 127, rq = tid >> 7, w = 2 << g;
;         const int ubase = samp ? rq * 47 : 0, tl0 = samp ? 0 : 32 * rq, pos0 = samp ? PAST : (t0 + 32 * rq);
;         const LAS float* Uc = U + (ubase + 15 + tl0) * 128 + c;
;         float wsum = 0.f;
;         for (int j = 1; j < w; ++j) wsum += Uc[-j * 128];
;         for (int i = 0; i < 32; ++i) {
;             const float cur = Uc[i * 128]; wsum += cur;
;             const int cnt = min(w, pos0 + i + 1);
;             const float d = wsum / (float)cnt - cur;
;             Dm[(32 * rq + i) * 136 + c] = (bf16_t)(pk_bf16(d, 0.f) & 0xffffu);
;             wsum -= Uc[(i - (w - 1)) * 128];
;         }
.LBB0_623:
	ds_read_b32 v136, v135
	s_add_i32 s7, s7, -1
	v_add_u32_e32 v135, 0xfffffe00, v135
	s_cmp_lg_u32 s7, 0
	s_waitcnt lgkmcnt(0)
	v_add_f32_e32 v134, v134, v136
	s_cbranch_scc1 .LBB0_623
	v_lshlrev_b32_e32 v135, 2, v133
	v_add3_u32 v132, 0, v132, v135
	v_add_u32_e32 v130, s16, v130
	v_or_b32_e32 v130, 1, v130
	v_mov_b32_e32 v135, 0x401
	v_cndmask_b32_e64 v130, v130, v135, s[0:1]
	v_lshlrev_b32_e32 v133, 1, v133
	v_readlane_b32 s7, v252, 35
	s_lshl_b32 s50, s13, 8
	s_add_i32 s12, s12, s34
	s_movk_i32 s0, 0x2200
	v_mul_lo_u32 v131, v131, s0
	s_lshl_b32 s0, 0xfffffc00, s13
	v_add3_u32 v131, s7, v133, v131
	v_add_u32_e32 v133, s0, v132
	ds_read2st64_b32 v[206:207], v132 offset0:0 offset1:2
	ds_read2st64_b32 v[168:169], v133 offset0:2 offset1:4
	ds_read2st64_b32 v[208:209], v132 offset0:4 offset1:6
	ds_read2st64_b32 v[170:171], v133 offset0:6 offset1:8
	ds_read2st64_b32 v[210:211], v132 offset0:8 offset1:10
	ds_read2st64_b32 v[172:173], v133 offset0:10 offset1:12
	ds_read2st64_b32 v[212:213], v132 offset0:12 offset1:14
	ds_read2st64_b32 v[174:175], v133 offset0:14 offset1:16
	v_mov_b32_e32 v240, v130
	v_min_i32_e32 v240, s6, v240
	v_cvt_f32_i32_e32 v240, v240
	v_rcp_f32_e32 v241, v240
	s_waitcnt lgkmcnt(7)
	v_add_f32_e32 v134, v134, v206
	v_mul_f32_e32 v136, v134, v241
	v_fma_f32 v137, -v240, v136, v134
	v_fmac_f32_e32 v136, v137, v241
	v_sub_f32_e32 v137, v136, v206
	v_cvt_pk_bf16_f32 v137, v137, s0
	ds_write_b16 v131, v137
	s_waitcnt lgkmcnt(7)
	v_sub_f32_e32 v134, v134, v168
	v_add_u32_e32 v242, 1, v130
	v_min_i32_e32 v242, s6, v242
	v_cvt_f32_i32_e32 v242, v242
	v_rcp_f32_e32 v243, v242
	v_add_f32_e32 v134, v134, v207
	v_mul_f32_e32 v138, v134, v243
	v_fma_f32 v139, -v242, v138, v134
	v_fmac_f32_e32 v138, v139, v243
	v_sub_f32_e32 v139, v138, v207
	v_cvt_pk_bf16_f32 v139, v139, s0
	ds_write_b16 v131, v139 offset:272
	v_sub_f32_e32 v134, v134, v169
	ds_read2st64_b32 v[214:215], v132 offset0:16 offset1:18
	ds_read2st64_b32 v[176:177], v133 offset0:18 offset1:20
	v_add_u32_e32 v244, 2, v130
	v_min_i32_e32 v244, s6, v244
	v_cvt_f32_i32_e32 v244, v244
	v_rcp_f32_e32 v245, v244
	s_waitcnt lgkmcnt(9)
	v_add_f32_e32 v134, v134, v208
	v_mul_f32_e32 v140, v134, v245
	v_fma_f32 v141, -v244, v140, v134
	v_fmac_f32_e32 v140, v141, v245
	v_sub_f32_e32 v141, v140, v208
	v_cvt_pk_bf16_f32 v141, v141, s0
	ds_write_b16 v131, v141 offset:544
	s_waitcnt lgkmcnt(9)
	v_sub_f32_e32 v134, v134, v170
	v_add_u32_e32 v246, 3, v130
	v_min_i32_e32 v246, s6, v246
	v_cvt_f32_i32_e32 v246, v246
	v_rcp_f32_e32 v247, v246
	v_add_f32_e32 v134, v134, v209
	v_mul_f32_e32 v136, v134, v247
	v_fma_f32 v137, -v246, v136, v134
	v_fmac_f32_e32 v136, v137, v247
	v_sub_f32_e32 v137, v136, v209
	v_cvt_pk_bf16_f32 v137, v137, s0
	ds_write_b16 v131, v137 offset:816
	v_sub_f32_e32 v134, v134, v171
	ds_read2st64_b32 v[216:217], v132 offset0:20 offset1:22
	ds_read2st64_b32 v[178:179], v133 offset0:22 offset1:24
	v_add_u32_e32 v248, 4, v130
	v_min_i32_e32 v248, s6, v248
	v_cvt_f32_i32_e32 v248, v248
	v_rcp_f32_e32 v249, v248
	s_waitcnt lgkmcnt(11)
	v_add_f32_e32 v134, v134, v210
	v_mul_f32_e32 v138, v134, v249
	v_fma_f32 v139, -v248, v138, v134
	v_fmac_f32_e32 v138, v139, v249
	v_sub_f32_e32 v139, v138, v210
	v_cvt_pk_bf16_f32 v139, v139, s0
	ds_write_b16 v131, v139 offset:1088
	s_waitcnt lgkmcnt(11)
	v_sub_f32_e32 v134, v134, v172
	v_add_u32_e32 v250, 5, v130
	v_min_i32_e32 v250, s6, v250
	v_cvt_f32_i32_e32 v250, v250
	v_rcp_f32_e32 v251, v250
	v_add_f32_e32 v134, v134, v211
	v_mul_f32_e32 v140, v134, v251
	v_fma_f32 v141, -v250, v140, v134
	v_fmac_f32_e32 v140, v141, v251
	v_sub_f32_e32 v141, v140, v211
	v_cvt_pk_bf16_f32 v141, v141, s0
	ds_write_b16 v131, v141 offset:1360
	v_sub_f32_e32 v134, v134, v173
	ds_read2st64_b32 v[218:219], v132 offset0:24 offset1:26
	ds_read2st64_b32 v[180:181], v133 offset0:26 offset1:28
	v_add_u32_e32 v240, 6, v130
	v_min_i32_e32 v240, s6, v240
	v_cvt_f32_i32_e32 v240, v240
	v_rcp_f32_e32 v241, v240
	s_waitcnt lgkmcnt(13)
	v_add_f32_e32 v134, v134, v212
	v_mul_f32_e32 v136, v134, v241
	v_fma_f32 v137, -v240, v136, v134
	v_fmac_f32_e32 v136, v137, v241
	v_sub_f32_e32 v137, v136, v212
	v_cvt_pk_bf16_f32 v137, v137, s0
	ds_write_b16 v131, v137 offset:1632
	s_waitcnt lgkmcnt(13)
	v_sub_f32_e32 v134, v134, v174
	v_add_u32_e32 v242, 7, v130
	v_min_i32_e32 v242, s6, v242
	v_cvt_f32_i32_e32 v242, v242
	v_rcp_f32_e32 v243, v242
	v_add_f32_e32 v134, v134, v213
	v_mul_f32_e32 v138, v134, v243
	v_fma_f32 v139, -v242, v138, v134
	v_fmac_f32_e32 v138, v139, v243
	v_sub_f32_e32 v139, v138, v213
	v_cvt_pk_bf16_f32 v139, v139, s0
	ds_write_b16 v131, v139 offset:1904
	v_sub_f32_e32 v134, v134, v175
	s_waitcnt lgkmcnt(10)
	ds_read2st64_b32 v[220:221], v132 offset0:28 offset1:30
	ds_read2st64_b32 v[182:183], v133 offset0:30 offset1:32
	v_add_u32_e32 v244, 8, v130
	v_min_i32_e32 v244, s6, v244
	v_cvt_f32_i32_e32 v244, v244
	v_rcp_f32_e32 v245, v244
	v_add_f32_e32 v134, v134, v214
	v_mul_f32_e32 v140, v134, v245
	v_fma_f32 v141, -v244, v140, v134
	v_fmac_f32_e32 v140, v141, v245
	v_sub_f32_e32 v141, v140, v214
	v_cvt_pk_bf16_f32 v141, v141, s0
	ds_write_b16 v131, v141 offset:2176
	v_sub_f32_e32 v134, v134, v176
	v_add_u32_e32 v246, 9, v130
	v_min_i32_e32 v246, s6, v246
	v_cvt_f32_i32_e32 v246, v246
	v_rcp_f32_e32 v247, v246
	v_add_f32_e32 v134, v134, v215
	v_mul_f32_e32 v136, v134, v247
	v_fma_f32 v137, -v246, v136, v134
	v_fmac_f32_e32 v136, v137, v247
	v_sub_f32_e32 v137, v136, v215
	v_cvt_pk_bf16_f32 v137, v137, s0
	ds_write_b16 v131, v137 offset:2448
	v_sub_f32_e32 v134, v134, v177
	s_waitcnt lgkmcnt(10)
; __device__ __forceinline__ unsigned pk_bf16(float lo, float hi) { const f32x2_t v = {lo, hi}; const bf16x2_t b = __builtin_convertvector(v, bf16x2_t); return __builtin_bit_cast(unsigned, b); }
; __device__ __forceinline__ void pool_unit(int tile, int g, const bf16_t* QKVU, const float* state_pool, const bf16_t* POOLWT, bf16_t* MIX, LAS unsigned char* lds) {
;     ...
;         for (int i = 0; i < 32; ++i) {
;             const float cur = Uc[i * 128]; wsum += cur;
;             const int cnt = min(w, pos0 + i + 1);
;             const float d = wsum / (float)cnt - cur;
;             Dm[(32 * rq + i) * 136 + c] = (bf16_t)(pk_bf16(d, 0.f) & 0xffffu);
;             wsum -= Uc[(i - (w - 1)) * 128];
;         }
	ds_read2st64_b32 v[222:223], v132 offset0:32 offset1:34
	ds_read2st64_b32 v[184:185], v133 offset0:34 offset1:36
	v_add_u32_e32 v248, 10, v130
	v_min_i32_e32 v248, s6, v248
	v_cvt_f32_i32_e32 v248, v248
	v_rcp_f32_e32 v249, v248
	v_add_f32_e32 v134, v134, v216
	v_mul_f32_e32 v138, v134, v249
	v_fma_f32 v139, -v248, v138, v134
	v_fmac_f32_e32 v138, v139, v249
	v_sub_f32_e32 v139, v138, v216
	v_cvt_pk_bf16_f32 v139, v139, s0
	ds_write_b16 v131, v139 offset:2720
	v_sub_f32_e32 v134, v134, v178
	v_add_u32_e32 v250, 11, v130
	v_min_i32_e32 v250, s6, v250
	v_cvt_f32_i32_e32 v250, v250
	v_rcp_f32_e32 v251, v250
	v_add_f32_e32 v134, v134, v217
	v_mul_f32_e32 v140, v134, v251
	v_fma_f32 v141, -v250, v140, v134
	v_fmac_f32_e32 v140, v141, v251
	v_sub_f32_e32 v141, v140, v217
	v_cvt_pk_bf16_f32 v141, v141, s0
	ds_write_b16 v131, v141 offset:2992
	v_sub_f32_e32 v134, v134, v179
	s_waitcnt lgkmcnt(10)
	ds_read2st64_b32 v[224:225], v132 offset0:36 offset1:38
	ds_read2st64_b32 v[186:187], v133 offset0:38 offset1:40
	v_add_u32_e32 v240, 12, v130
	v_min_i32_e32 v240, s6, v240
	v_cvt_f32_i32_e32 v240, v240
	v_rcp_f32_e32 v241, v240
	v_add_f32_e32 v134, v134, v218
	v_mul_f32_e32 v136, v134, v241
	v_fma_f32 v137, -v240, v136, v134
	v_fmac_f32_e32 v136, v137, v241
	v_sub_f32_e32 v137, v136, v218
	v_cvt_pk_bf16_f32 v137, v137, s0
	ds_write_b16 v131, v137 offset:3264
	v_sub_f32_e32 v134, v134, v180
	v_add_u32_e32 v242, 13, v130
	v_min_i32_e32 v242, s6, v242
	v_cvt_f32_i32_e32 v242, v242
	v_rcp_f32_e32 v243, v242
	v_add_f32_e32 v134, v134, v219
	v_mul_f32_e32 v138, v134, v243
	v_fma_f32 v139, -v242, v138, v134
	v_fmac_f32_e32 v138, v139, v243
	v_sub_f32_e32 v139, v138, v219
	v_cvt_pk_bf16_f32 v139, v139, s0
	ds_write_b16 v131, v139 offset:3536
	v_sub_f32_e32 v134, v134, v181
	s_waitcnt lgkmcnt(10)
	ds_read2st64_b32 v[226:227], v132 offset0:40 offset1:42
	ds_read2st64_b32 v[188:189], v133 offset0:42 offset1:44
	v_add_u32_e32 v244, 14, v130
	v_min_i32_e32 v244, s6, v244
	v_cvt_f32_i32_e32 v244, v244
	v_rcp_f32_e32 v245, v244
	v_add_f32_e32 v134, v134, v220
	v_mul_f32_e32 v140, v134, v245
	v_fma_f32 v141, -v244, v140, v134
	v_fmac_f32_e32 v140, v141, v245
	v_sub_f32_e32 v141, v140, v220
	v_cvt_pk_bf16_f32 v141, v141, s0
	ds_write_b16 v131, v141 offset:3808
	v_sub_f32_e32 v134, v134, v182
	v_add_u32_e32 v246, 15, v130
	v_min_i32_e32 v246, s6, v246
	v_cvt_f32_i32_e32 v246, v246
	v_rcp_f32_e32 v247, v246
	v_add_f32_e32 v134, v134, v221
	v_mul_f32_e32 v136, v134, v247
	v_fma_f32 v137, -v246, v136, v134
	v_fmac_f32_e32 v136, v137, v247
	v_sub_f32_e32 v137, v136, v221
	v_cvt_pk_bf16_f32 v137, v137, s0
	ds_write_b16 v131, v137 offset:4080
	v_sub_f32_e32 v134, v134, v183
	s_waitcnt lgkmcnt(10)
	ds_read2st64_b32 v[228:229], v132 offset0:44 offset1:46
	ds_read2st64_b32 v[190:191], v133 offset0:46 offset1:48
	v_add_u32_e32 v248, 16, v130
	v_min_i32_e32 v248, s6, v248
	v_cvt_f32_i32_e32 v248, v248
	v_rcp_f32_e32 v249, v248
	v_add_f32_e32 v134, v134, v222
	v_mul_f32_e32 v138, v134, v249
	v_fma_f32 v139, -v248, v138, v134
	v_fmac_f32_e32 v138, v139, v249
	v_sub_f32_e32 v139, v138, v222
	v_cvt_pk_bf16_f32 v139, v139, s0
	ds_write_b16 v131, v139 offset:4352
	v_sub_f32_e32 v134, v134, v184
	v_add_u32_e32 v250, 17, v130
	v_min_i32_e32 v250, s6, v250
	v_cvt_f32_i32_e32 v250, v250
	v_rcp_f32_e32 v251, v250
	v_add_f32_e32 v134, v134, v223
	v_mul_f32_e32 v140, v134, v251
	v_fma_f32 v141, -v250, v140, v134
	v_fmac_f32_e32 v140, v141, v251
	v_sub_f32_e32 v141, v140, v223
	v_cvt_pk_bf16_f32 v141, v141, s0
	ds_write_b16 v131, v141 offset:4624
	v_sub_f32_e32 v134, v134, v185
	s_waitcnt lgkmcnt(10)
	ds_read2st64_b32 v[230:231], v132 offset0:48 offset1:50
	ds_read2st64_b32 v[192:193], v133 offset0:50 offset1:52
	v_add_u32_e32 v240, 18, v130
	v_min_i32_e32 v240, s6, v240
	v_cvt_f32_i32_e32 v240, v240
	v_rcp_f32_e32 v241, v240
	v_add_f32_e32 v134, v134, v224
	v_mul_f32_e32 v136, v134, v241
	v_fma_f32 v137, -v240, v136, v134
	v_fmac_f32_e32 v136, v137, v241
	v_sub_f32_e32 v137, v136, v224
	v_cvt_pk_bf16_f32 v137, v137, s0
	ds_write_b16 v131, v137 offset:4896
	v_sub_f32_e32 v134, v134, v186
	v_add_u32_e32 v242, 19, v130
	v_min_i32_e32 v242, s6, v242
	v_cvt_f32_i32_e32 v242, v242
	v_rcp_f32_e32 v243, v242
	v_add_f32_e32 v134, v134, v225
	v_mul_f32_e32 v138, v134, v243
	v_fma_f32 v139, -v242, v138, v134
	v_fmac_f32_e32 v138, v139, v243
	v_sub_f32_e32 v139, v138, v225
	v_cvt_pk_bf16_f32 v139, v139, s0
	ds_write_b16 v131, v139 offset:5168
	v_sub_f32_e32 v134, v134, v187
	s_waitcnt lgkmcnt(10)
	ds_read2st64_b32 v[232:233], v132 offset0:52 offset1:54
	ds_read2st64_b32 v[194:195], v133 offset0:54 offset1:56
	v_add_u32_e32 v244, 20, v130
	v_min_i32_e32 v244, s6, v244
	v_cvt_f32_i32_e32 v244, v244
	v_rcp_f32_e32 v245, v244
	v_add_f32_e32 v134, v134, v226
	v_mul_f32_e32 v140, v134, v245
	v_fma_f32 v141, -v244, v140, v134
	v_fmac_f32_e32 v140, v141, v245
	v_sub_f32_e32 v141, v140, v226
	v_cvt_pk_bf16_f32 v141, v141, s0
	ds_write_b16 v131, v141 offset:5440
	v_sub_f32_e32 v134, v134, v188
	v_add_u32_e32 v246, 21, v130
	v_min_i32_e32 v246, s6, v246
	v_cvt_f32_i32_e32 v246, v246
	v_rcp_f32_e32 v247, v246
	v_add_f32_e32 v134, v134, v227
	v_mul_f32_e32 v136, v134, v247
	v_fma_f32 v137, -v246, v136, v134
	v_fmac_f32_e32 v136, v137, v247
	v_sub_f32_e32 v137, v136, v227
	v_cvt_pk_bf16_f32 v137, v137, s0
	ds_write_b16 v131, v137 offset:5712
	v_sub_f32_e32 v134, v134, v189
	s_waitcnt lgkmcnt(10)
; __device__ __forceinline__ unsigned pk_bf16(float lo, float hi) { const f32x2_t v = {lo, hi}; const bf16x2_t b = __builtin_convertvector(v, bf16x2_t); return __builtin_bit_cast(unsigned, b); }
; __device__ __forceinline__ void pool_unit(int tile, int g, const bf16_t* QKVU, const float* state_pool, const bf16_t* POOLWT, bf16_t* MIX, LAS unsigned char* lds) {
;     ...
;         for (int i = 0; i < 32; ++i) {
;             const float cur = Uc[i * 128]; wsum += cur;
;             const int cnt = min(w, pos0 + i + 1);
;             const float d = wsum / (float)cnt - cur;
;             Dm[(32 * rq + i) * 136 + c] = (bf16_t)(pk_bf16(d, 0.f) & 0xffffu);
;             wsum -= Uc[(i - (w - 1)) * 128];
;         }
;     }
;     __syncthreads();
	ds_read2st64_b32 v[234:235], v132 offset0:56 offset1:58
	ds_read2st64_b32 v[196:197], v133 offset0:58 offset1:60
	v_add_u32_e32 v248, 22, v130
	v_min_i32_e32 v248, s6, v248
	v_cvt_f32_i32_e32 v248, v248
	v_rcp_f32_e32 v249, v248
	v_add_f32_e32 v134, v134, v228
	v_mul_f32_e32 v138, v134, v249
	v_fma_f32 v139, -v248, v138, v134
	v_fmac_f32_e32 v138, v139, v249
	v_sub_f32_e32 v139, v138, v228
	v_cvt_pk_bf16_f32 v139, v139, s0
	ds_write_b16 v131, v139 offset:5984
	v_sub_f32_e32 v134, v134, v190
	v_add_u32_e32 v250, 23, v130
	v_min_i32_e32 v250, s6, v250
	v_cvt_f32_i32_e32 v250, v250
	v_rcp_f32_e32 v251, v250
	v_add_f32_e32 v134, v134, v229
	v_mul_f32_e32 v140, v134, v251
	v_fma_f32 v141, -v250, v140, v134
	v_fmac_f32_e32 v140, v141, v251
	v_sub_f32_e32 v141, v140, v229
	v_cvt_pk_bf16_f32 v141, v141, s0
	ds_write_b16 v131, v141 offset:6256
	v_sub_f32_e32 v134, v134, v191
	s_waitcnt lgkmcnt(10)
	ds_read2st64_b32 v[236:237], v132 offset0:60 offset1:62
	ds_read_b32 v238, v133 offset:15872
	v_add_u32_e32 v240, 24, v130
	v_min_i32_e32 v240, s6, v240
	v_cvt_f32_i32_e32 v240, v240
	v_rcp_f32_e32 v241, v240
	v_add_f32_e32 v134, v134, v230
	v_mul_f32_e32 v136, v134, v241
	v_fma_f32 v137, -v240, v136, v134
	v_fmac_f32_e32 v136, v137, v241
	v_sub_f32_e32 v137, v136, v230
	v_cvt_pk_bf16_f32 v137, v137, s0
	ds_write_b16 v131, v137 offset:6528
	v_sub_f32_e32 v134, v134, v192
	v_add_u32_e32 v242, 25, v130
	v_min_i32_e32 v242, s6, v242
	v_cvt_f32_i32_e32 v242, v242
	v_rcp_f32_e32 v243, v242
	v_add_f32_e32 v134, v134, v231
	v_mul_f32_e32 v138, v134, v243
	v_fma_f32 v139, -v242, v138, v134
	v_fmac_f32_e32 v138, v139, v243
	v_sub_f32_e32 v139, v138, v231
	v_cvt_pk_bf16_f32 v139, v139, s0
	ds_write_b16 v131, v139 offset:6800
	v_sub_f32_e32 v134, v134, v193
	v_add_u32_e32 v244, 26, v130
	v_min_i32_e32 v244, s6, v244
	v_cvt_f32_i32_e32 v244, v244
	v_rcp_f32_e32 v245, v244
	s_waitcnt lgkmcnt(11)
	v_add_f32_e32 v134, v134, v232
	v_mul_f32_e32 v140, v134, v245
	v_fma_f32 v141, -v244, v140, v134
	v_fmac_f32_e32 v140, v141, v245
	v_sub_f32_e32 v141, v140, v232
	v_cvt_pk_bf16_f32 v141, v141, s0
	ds_write_b16 v131, v141 offset:7072
	s_waitcnt lgkmcnt(11)
	v_sub_f32_e32 v134, v134, v194
	v_add_u32_e32 v246, 27, v130
	v_min_i32_e32 v246, s6, v246
	v_cvt_f32_i32_e32 v246, v246
	v_rcp_f32_e32 v247, v246
	v_add_f32_e32 v134, v134, v233
	v_mul_f32_e32 v136, v134, v247
	v_fma_f32 v137, -v246, v136, v134
	v_fmac_f32_e32 v136, v137, v247
	v_sub_f32_e32 v137, v136, v233
	v_cvt_pk_bf16_f32 v137, v137, s0
	ds_write_b16 v131, v137 offset:7344
	v_sub_f32_e32 v134, v134, v195
	v_add_u32_e32 v248, 28, v130
	v_min_i32_e32 v248, s6, v248
	v_cvt_f32_i32_e32 v248, v248
	v_rcp_f32_e32 v249, v248
	s_waitcnt lgkmcnt(9)
	v_add_f32_e32 v134, v134, v234
	v_mul_f32_e32 v138, v134, v249
	v_fma_f32 v139, -v248, v138, v134
	v_fmac_f32_e32 v138, v139, v249
	v_sub_f32_e32 v139, v138, v234
	v_cvt_pk_bf16_f32 v139, v139, s0
	ds_write_b16 v131, v139 offset:7616
	s_waitcnt lgkmcnt(9)
	v_sub_f32_e32 v134, v134, v196
	v_add_u32_e32 v250, 29, v130
	v_min_i32_e32 v250, s6, v250
	v_cvt_f32_i32_e32 v250, v250
	v_rcp_f32_e32 v251, v250
	v_add_f32_e32 v134, v134, v235
	v_mul_f32_e32 v140, v134, v251
	v_fma_f32 v141, -v250, v140, v134
	v_fmac_f32_e32 v140, v141, v251
	v_sub_f32_e32 v141, v140, v235
	v_cvt_pk_bf16_f32 v141, v141, s0
	ds_write_b16 v131, v141 offset:7888
	v_sub_f32_e32 v134, v134, v197
	v_add_u32_e32 v240, 30, v130
	v_min_i32_e32 v240, s6, v240
	v_cvt_f32_i32_e32 v240, v240
	v_rcp_f32_e32 v241, v240
	s_waitcnt lgkmcnt(7)
	v_add_f32_e32 v134, v134, v236
	v_mul_f32_e32 v136, v134, v241
	v_fma_f32 v137, -v240, v136, v134
	v_fmac_f32_e32 v136, v137, v241
	v_sub_f32_e32 v137, v136, v236
	v_cvt_pk_bf16_f32 v137, v137, s0
	ds_write_b16 v131, v137 offset:8160
	s_waitcnt lgkmcnt(7)
	v_sub_f32_e32 v134, v134, v238
	v_add_u32_e32 v242, 31, v130
	v_min_i32_e32 v242, s6, v242
	v_cvt_f32_i32_e32 v242, v242
	v_rcp_f32_e32 v243, v242
	v_add_f32_e32 v134, v134, v237
	v_mul_f32_e32 v138, v134, v243
	v_fma_f32 v139, -v242, v138, v134
	v_fmac_f32_e32 v138, v139, v243
	v_sub_f32_e32 v139, v138, v237
	v_cvt_pk_bf16_f32 v139, v139, s0
	ds_write_b16 v131, v139 offset:8432
	s_movk_i32 s1, 0x110
	s_ashr_i32 s0, s15, 2
	s_and_b32 s0, s0, -16
	v_or_b32_e32 v130, s0, v167
	v_mul_lo_u32 v130, v130, s1
	v_add3_u32 v0, s7, v130, v0
	s_waitcnt lgkmcnt(0)
	s_barrier
; #define LAS __attribute__((address_space(3)))
; __device__ __forceinline__ unsigned pk_bf16(float lo, float hi) { const f32x2_t v = {lo, hi}; const bf16x2_t b = __builtin_convertvector(v, bf16x2_t); return __builtin_bit_cast(unsigned, b); }
; __device__ __forceinline__ void pool_unit(int tile, int g, const bf16_t* QKVU, const float* state_pool, const bf16_t* POOLWT, bf16_t* MIX, LAS unsigned char* lds) {
;     ...
;     {
;         f32x4 acc[8];
; #pragma unroll
;         for (int nf = 0; nf < 8; ++nf) acc[nf] = (f32x4){0.f, 0.f, 0.f, 0.f};
;         asm volatile("" : "+v"(wv[0][0]), "+v"(wv[0][1]), "+v"(wv[0][2]), "+v"(wv[0][3]), "+v"(wv[0][4]), "+v"(wv[0][5]), "+v"(wv[0][6]), "+v"(wv[0][7]),
;                      "+v"(wv[1][0]), "+v"(wv[1][1]), "+v"(wv[1][2]), "+v"(wv[1][3]), "+v"(wv[1][4]), "+v"(wv[1][5]), "+v"(wv[1][6]), "+v"(wv[1][7]));
;         asm volatile("" : "+v"(wv[2][0]), "+v"(wv[2][1]), "+v"(wv[2][2]), "+v"(wv[2][3]), "+v"(wv[2][4]), "+v"(wv[2][5]), "+v"(wv[2][6]), "+v"(wv[2][7]),
;                      "+v"(wv[3][0]), "+v"(wv[3][1]), "+v"(wv[3][2]), "+v"(wv[3][3]), "+v"(wv[3][4]), "+v"(wv[3][5]), "+v"(wv[3][6]), "+v"(wv[3][7]));
; #pragma unroll
;         for (int ks = 0; ks < 4; ++ks) {
;             const bf16x8 av = *(const LAS bf16x8*)(Dm + (16 * wid + fr) * 136 + 32 * ks + 8 * fq);
; #pragma unroll
;             for (int nf = 0; nf < 8; ++nf) acc[nf] = __builtin_amdgcn_mfma_f32_16x16x32_bf16(wv[ks][nf], av, acc[nf], 0, 0, 0);
;         }
;         const int row = r0 + 16 * wid + fr;
; #pragma unroll
;         for (int nf = 0; nf < 8; ++nf) { u32x2 w; w.x = pk_bf16(acc[nf][0], acc[nf][1]); w.y = pk_bf16(acc[nf][2], acc[nf][3]);
;             *(u32x2*)(MIX + (size_t)row * DM + 512 + g * 128 + 16 * nf + 4 * fq) = w; }
;     }
;     __syncthreads();
	s_waitcnt vmcnt(16)
	s_waitcnt vmcnt(0)
	ds_read_b128 v[130:133], v0
	s_waitcnt lgkmcnt(0)
	v_mfma_f32_16x16x32_bf16 v[126:129], v[126:129], v[130:133], 0
	s_add_i32 s0, s0, s14
	s_cmpk_gt_i32 s12, 0x81f
	v_mfma_f32_16x16x32_bf16 v[90:93], v[90:93], v[130:133], 0
	v_mfma_f32_16x16x32_bf16 v[94:97], v[94:97], v[130:133], 0
	v_mfma_f32_16x16x32_bf16 v[106:109], v[106:109], v[130:133], 0
	v_mfma_f32_16x16x32_bf16 v[110:113], v[110:113], v[130:133], 0
	v_mfma_f32_16x16x32_bf16 v[114:117], v[114:117], v[130:133], 0
	v_mfma_f32_16x16x32_bf16 v[118:121], v[118:121], v[130:133], 0
	v_mfma_f32_16x16x32_bf16 v[122:125], v[122:125], v[130:133], 0
	ds_read_b128 v[130:133], v0 offset:64
	s_waitcnt lgkmcnt(0)
	v_mfma_f32_16x16x32_bf16 v[38:41], v[38:41], v[130:133], v[90:93]
	s_nop 2
	ds_read_b128 v[90:93], v0 offset:128
	v_mfma_f32_16x16x32_bf16 v[34:37], v[34:37], v[130:133], v[126:129]
	v_mfma_f32_16x16x32_bf16 v[42:45], v[42:45], v[130:133], v[94:97]
	s_waitcnt lgkmcnt(0)
	v_mfma_f32_16x16x32_bf16 v[38:41], v[66:69], v[90:93], v[38:41]
	ds_read_b128 v[66:69], v0 offset:192
	v_lshlrev_b32_e32 v0, 3, v166
	v_mfma_f32_16x16x32_bf16 v[46:49], v[46:49], v[130:133], v[106:109]
	v_mfma_f32_16x16x32_bf16 v[34:37], v[102:105], v[90:93], v[34:37]
	v_mfma_f32_16x16x32_bf16 v[50:53], v[50:53], v[130:133], v[110:113]
	v_mfma_f32_16x16x32_bf16 v[54:57], v[54:57], v[130:133], v[114:117]
	v_mfma_f32_16x16x32_bf16 v[58:61], v[58:61], v[130:133], v[118:121]
	v_mfma_f32_16x16x32_bf16 v[42:45], v[70:73], v[90:93], v[42:45]
	v_mfma_f32_16x16x32_bf16 v[62:65], v[62:65], v[130:133], v[122:125]
	v_mfma_f32_16x16x32_bf16 v[46:49], v[74:77], v[90:93], v[46:49]
	s_waitcnt lgkmcnt(0)
	v_mfma_f32_16x16x32_bf16 v[2:5], v[2:5], v[66:69], v[34:37]
	s_nop 2
	v_or_b32_e32 v34, s0, v167
	v_mfma_f32_16x16x32_bf16 v[50:53], v[78:81], v[90:93], v[50:53]
	v_ashrrev_i32_e32 v35, 31, v34
	v_lshlrev_b64 v[34:35], 11, v[34:35]
	v_lshl_add_u64 v[34:35], s[52:53], 0, v[34:35]
	v_mfma_f32_16x16x32_bf16 v[54:57], v[82:85], v[90:93], v[54:57]
	v_lshl_add_u64 v[34:35], v[34:35], 0, s[50:51]
	v_lshl_add_u64 v[34:35], v[34:35], 0, v[0:1]
	v_cvt_pk_bf16_f32 v2, v2, v3
	v_mfma_f32_16x16x32_bf16 v[6:9], v[6:9], v[66:69], v[38:41]
	v_cvt_pk_bf16_f32 v3, v4, v5
	global_store_dwordx2 v[34:35], v[2:3], off offset:1024
	v_mfma_f32_16x16x32_bf16 v[58:61], v[86:89], v[90:93], v[58:61]
	v_mfma_f32_16x16x32_bf16 v[10:13], v[10:13], v[66:69], v[42:45]
	s_nop 3
	v_cvt_pk_bf16_f32 v2, v6, v7
	v_cvt_pk_bf16_f32 v3, v8, v9
	global_store_dwordx2 v[34:35], v[2:3], off offset:1056
	v_mfma_f32_16x16x32_bf16 v[62:65], v[98:101], v[90:93], v[62:65]
	v_mfma_f32_16x16x32_bf16 v[14:17], v[14:17], v[66:69], v[46:49]
	v_cvt_pk_bf16_f32 v2, v10, v11
	v_cvt_pk_bf16_f32 v3, v12, v13
	global_store_dwordx2 v[34:35], v[2:3], off offset:1088
	v_mfma_f32_16x16x32_bf16 v[18:21], v[18:21], v[66:69], v[50:53]
	v_mfma_f32_16x16x32_bf16 v[22:25], v[22:25], v[66:69], v[54:57]
	s_nop 2
	v_cvt_pk_bf16_f32 v2, v14, v15
	v_cvt_pk_bf16_f32 v3, v16, v17
	global_store_dwordx2 v[34:35], v[2:3], off offset:1120
	v_mfma_f32_16x16x32_bf16 v[26:29], v[26:29], v[66:69], v[58:61]
	v_cvt_pk_bf16_f32 v2, v18, v19
	v_cvt_pk_bf16_f32 v3, v20, v21
	global_store_dwordx2 v[34:35], v[2:3], off offset:1152
	v_mfma_f32_16x16x32_bf16 v[30:33], v[30:33], v[66:69], v[62:65]
	v_cvt_pk_bf16_f32 v2, v22, v23
	v_cvt_pk_bf16_f32 v3, v24, v25
	global_store_dwordx2 v[34:35], v[2:3], off offset:1184
	s_nop 0
	v_cvt_pk_bf16_f32 v2, v26, v27
	v_cvt_pk_bf16_f32 v3, v28, v29
	global_store_dwordx2 v[34:35], v[2:3], off offset:1216
	s_nop 0
	v_cvt_pk_bf16_f32 v2, v30, v31
	v_cvt_pk_bf16_f32 v3, v32, v33
	global_store_dwordx2 v[34:35], v[2:3], off offset:1248
	s_barrier
	s_cbranch_scc0 .LBB0_591
